# sparse attention step: second token tile's QK MFMAs and first tile's PV MFMAs woven into the softmax VALU stream; partial blocks masked with one unsigned range compare per key
# speedup vs baseline: 1.0114x; 1.0015x over previous
.LBB0_2063:
	s_or_b64 exec, exec, s[0:1]
	s_cmpk_gt_i32 s90, 0x3ff
	v_readlane_b32 s68, v251, 50
	v_readlane_b32 s69, v251, 51
	s_waitcnt lgkmcnt(0)
	s_barrier
	s_cbranch_scc1 .LBB0_2167
	v_readlane_b32 s0, v251, 7
	v_and_b32_e32 v112, 15, v152
	v_lshrrev_b32_e32 v113, 4, v152
	s_nop 1
	s_and_b32 s34, s0, 3
	s_lshr_b32 s35, s0, 2
	v_lshrrev_b32_e32 v220, 3, v153
	v_and_b32_e32 v221, 7, v153
	v_mul_u32_u24_e32 v114, 0x90, v220
	v_lshl_add_u32 v114, v221, 4, v114
	v_mul_u32_u24_e32 v117, 0x600, v220
	v_lshl_add_u32 v117, v221, 4, v117
	v_lshlrev_b32_e32 v118, 12, v220
	v_lshl_add_u32 v118, v221, 4, v118
	v_mul_u32_u24_e32 v115, 0x90, v112
	v_lshl_add_u32 v116, v113, 3, v115
	v_lshl_add_u32 v115, v113, 4, v115
	v_mov_b32_e32 v226, 0xf149f2ca
	v_mov_b32_e32 v227, 0x7f61b1e6
	v_mov_b32_e32 v238, 0
	v_mov_b32_e32 v224, 0xff800000
	s_mov_b32 s26, s90
	s_mov_b32 s27, 0

.Lnsa_brd_2:
	s_cmp_eq_u32 s37, 1
	s_mov_b32 s45, 0x7fffffff
	s_cselect_b32 s45, 0x200, s45
	v_mov_b32_e32 v80, v226
	v_mov_b32_e32 v82, 0
	v_mov_b32_e32 v48, 0
	v_mov_b32_e32 v49, 0
	v_mov_b32_e32 v50, 0
	v_mov_b32_e32 v51, 0
	v_mov_b32_e32 v52, 0
	v_mov_b32_e32 v53, 0
	v_mov_b32_e32 v54, 0
	v_mov_b32_e32 v55, 0
	v_mov_b32_e32 v56, 0
	v_mov_b32_e32 v57, 0
	v_mov_b32_e32 v58, 0
	v_mov_b32_e32 v59, 0
	v_mov_b32_e32 v60, 0
	v_mov_b32_e32 v61, 0
	v_mov_b32_e32 v62, 0
	v_mov_b32_e32 v63, 0
	v_mov_b32_e32 v81, v226
	v_mov_b32_e32 v83, 0
	v_mov_b32_e32 v64, 0
	v_mov_b32_e32 v65, 0
	v_mov_b32_e32 v66, 0
	v_mov_b32_e32 v67, 0
	v_mov_b32_e32 v68, 0
	v_mov_b32_e32 v69, 0
	v_mov_b32_e32 v70, 0
	v_mov_b32_e32 v71, 0
	v_mov_b32_e32 v72, 0
	v_mov_b32_e32 v73, 0
	v_mov_b32_e32 v74, 0
	v_mov_b32_e32 v75, 0
	v_mov_b32_e32 v76, 0
	v_mov_b32_e32 v77, 0
	v_mov_b32_e32 v78, 0
	v_mov_b32_e32 v79, 0
	s_ff1_i32_b32 s40, s38
	s_add_i32 s65, s38, -1
	s_and_b32 s38, s38, s65
	s_ff1_i32_b32 s41, s38
	s_add_i32 s65, s38, -1
	s_and_b32 s38, s38, s65
	s_ff1_i32_b32 s42, s38
	s_add_i32 s65, s38, -1
	s_and_b32 s38, s38, s65
	s_cmp_eq_u32 s37, 1
	s_cbranch_scc0 .Lnsa_nopre_3
	v_mov_b32_e32 v88, v192
	v_mov_b32_e32 v92, v196
	v_mov_b32_e32 v89, v193
	v_mov_b32_e32 v93, v197
	v_mov_b32_e32 v90, v194
	v_mov_b32_e32 v94, v198
	v_mov_b32_e32 v91, v195
	v_mov_b32_e32 v95, v199
	s_branch .Lnsa_have0_4

.Lnsa_inter_16:
	s_mov_b32 s64, 0
	s_branch .Lnsa_go_17
.Lnsa_part_15:
	s_mov_b32 s64, 1
	v_lshlrev_b32_e32 v220, 2, v113
	v_add_u32_e32 v220, s44, v220
	v_sub_u32_e32 v120, v86, v220
	v_sub_u32_e32 v121, v87, v220
.Lnsa_go_17:
	v_add_u32_e32 v225, s50, v115
	ds_read_b128 v[160:163], v225 offset:0
	ds_read_b128 v[164:167], v225 offset:64
	ds_read_b128 v[168:171], v225 offset:2304
	ds_read_b128 v[172:175], v225 offset:2368
	ds_read_b128 v[176:179], v225 offset:4608
	ds_read_b128 v[180:183], v225 offset:4672
	ds_read_b128 v[184:187], v225 offset:6912
	ds_read_b128 v[188:191], v225 offset:6976
	v_add_u32_e32 v247, s50, v116
	s_waitcnt lgkmcnt(0)
	v_mfma_f32_16x16x32_bf16 v[124:127], v[160:163], v[0:3], 0
	v_mfma_f32_16x16x32_bf16 v[128:131], v[168:171], v[0:3], 0
	v_mfma_f32_16x16x32_bf16 v[132:135], v[176:179], v[0:3], 0
	v_mfma_f32_16x16x32_bf16 v[136:139], v[184:187], v[0:3], 0
	v_mfma_f32_16x16x32_bf16 v[124:127], v[164:167], v[4:7], v[124:127]
	v_mfma_f32_16x16x32_bf16 v[128:131], v[172:175], v[4:7], v[128:131]
	v_mfma_f32_16x16x32_bf16 v[132:135], v[180:183], v[4:7], v[132:135]
	v_mfma_f32_16x16x32_bf16 v[136:139], v[188:191], v[4:7], v[136:139]
	s_nop 7
	s_cmp_eq_u32 s64, 0
	s_cbranch_scc1 .Lnsa_nm_18
	v_cndmask_b32_e64 v240, -1, v120, s[60:61]
	v_subrev_u32_e32 v220, 0, v240
	v_subrev_u32_e32 v221, 1, v240
	v_subrev_u32_e32 v222, 2, v240
	v_subrev_u32_e32 v223, 3, v240
	v_cmp_gt_u32_e64 s[52:53], s45, v220
	v_cmp_gt_u32_e64 s[54:55], s45, v221
	v_cmp_gt_u32_e64 s[56:57], s45, v222
	v_cmp_gt_u32_e64 s[58:59], s45, v223
	v_cndmask_b32_e64 v124, v224, v124, s[52:53]
	v_cndmask_b32_e64 v125, v224, v125, s[54:55]
	v_cndmask_b32_e64 v126, v224, v126, s[56:57]
	v_cndmask_b32_e64 v127, v224, v127, s[58:59]
	v_subrev_u32_e32 v220, 16, v240
	v_subrev_u32_e32 v221, 17, v240
	v_subrev_u32_e32 v222, 18, v240
	v_subrev_u32_e32 v223, 19, v240
	v_cmp_gt_u32_e64 s[52:53], s45, v220
	v_cmp_gt_u32_e64 s[54:55], s45, v221
	v_cmp_gt_u32_e64 s[56:57], s45, v222
	v_cmp_gt_u32_e64 s[58:59], s45, v223
	v_cndmask_b32_e64 v128, v224, v128, s[52:53]
	v_cndmask_b32_e64 v129, v224, v129, s[54:55]
	v_cndmask_b32_e64 v130, v224, v130, s[56:57]
	v_cndmask_b32_e64 v131, v224, v131, s[58:59]
	v_subrev_u32_e32 v220, 32, v240
	v_subrev_u32_e32 v221, 33, v240
	v_subrev_u32_e32 v222, 34, v240
	v_subrev_u32_e32 v223, 35, v240
	v_cmp_gt_u32_e64 s[52:53], s45, v220
	v_cmp_gt_u32_e64 s[54:55], s45, v221
	v_cmp_gt_u32_e64 s[56:57], s45, v222
	v_cmp_gt_u32_e64 s[58:59], s45, v223
	v_cndmask_b32_e64 v132, v224, v132, s[52:53]
	v_cndmask_b32_e64 v133, v224, v133, s[54:55]
	v_cndmask_b32_e64 v134, v224, v134, s[56:57]
	v_cndmask_b32_e64 v135, v224, v135, s[58:59]
	v_subrev_u32_e32 v220, 48, v240
	v_subrev_u32_e32 v221, 49, v240
	v_subrev_u32_e32 v222, 50, v240
	v_subrev_u32_e32 v223, 51, v240
	v_cmp_gt_u32_e64 s[52:53], s45, v220
	v_cmp_gt_u32_e64 s[54:55], s45, v221
	v_cmp_gt_u32_e64 s[56:57], s45, v222
	v_cmp_gt_u32_e64 s[58:59], s45, v223
	v_cndmask_b32_e64 v136, v224, v136, s[52:53]
	v_cndmask_b32_e64 v137, v224, v137, s[54:55]
	v_cndmask_b32_e64 v138, v224, v138, s[56:57]
	v_cndmask_b32_e64 v139, v224, v139, s[58:59]
.Lnsa_nm_18:
	v_mfma_f32_16x16x32_bf16 v[140:143], v[160:163], v[8:11], 0
	v_max3_f32 v220, v124, v125, v126
	v_max3_f32 v220, v220, v127, v128
	v_max3_f32 v220, v220, v129, v130
	v_max3_f32 v220, v220, v131, v132
	v_mfma_f32_16x16x32_bf16 v[144:147], v[168:171], v[8:11], 0
	v_max3_f32 v220, v220, v133, v134
	v_max3_f32 v220, v220, v135, v136
	v_max3_f32 v220, v220, v137, v138
	v_max3_f32 v220, v220, v139, v226
	v_mfma_f32_16x16x32_bf16 v[148:151], v[176:179], v[8:11], 0
	v_cndmask_b32_e64 v220, v226, v220, s[60:61]
	v_mov_b32_e32 v221, v220
	s_nop 1
	v_permlane16_swap_b32_e32 v220, v221
	v_mfma_f32_16x16x32_bf16 v[154:157], v[184:187], v[8:11], 0
	v_max_f32_e32 v220, v220, v221
	v_mov_b32_e32 v221, v220
	s_nop 1
	v_permlane32_swap_b32_e32 v220, v221
	v_mfma_f32_16x16x32_bf16 v[140:143], v[164:167], v[12:15], v[140:143]
	v_max_f32_e32 v220, v220, v221
	v_max_f32_e32 v222, v80, v220
	v_sub_f32_e32 v223, v80, v222
	v_exp_f32_e32 v228, v223
	v_mfma_f32_16x16x32_bf16 v[144:147], v[172:175], v[12:15], v[144:147]
	v_mov_b32_e32 v80, v222
	v_cndmask_b32_e64 v222, v227, v222, s[60:61]
	v_sub_f32_e32 v124, v124, v222
	v_sub_f32_e32 v125, v125, v222
	v_mfma_f32_16x16x32_bf16 v[148:151], v[180:183], v[12:15], v[148:151]
	v_sub_f32_e32 v126, v126, v222
	v_sub_f32_e32 v127, v127, v222
	v_sub_f32_e32 v128, v128, v222
	v_sub_f32_e32 v129, v129, v222
	v_mfma_f32_16x16x32_bf16 v[154:157], v[188:191], v[12:15], v[154:157]
	v_sub_f32_e32 v130, v130, v222
	v_sub_f32_e32 v131, v131, v222
	v_sub_f32_e32 v132, v132, v222
	v_sub_f32_e32 v133, v133, v222
	v_sub_f32_e32 v134, v134, v222
	v_sub_f32_e32 v135, v135, v222
	v_sub_f32_e32 v136, v136, v222
	v_sub_f32_e32 v137, v137, v222
	ds_read_b64 v[160:161], v247 offset:9216
	v_sub_f32_e32 v138, v138, v222
	v_sub_f32_e32 v139, v139, v222
	ds_read_b64 v[162:163], v247 offset:9248
	v_exp_f32_e32 v124, v124
	v_exp_f32_e32 v125, v125
	ds_read_b64 v[164:165], v247 offset:9280
	v_exp_f32_e32 v126, v126
	v_exp_f32_e32 v127, v127
	ds_read_b64 v[166:167], v247 offset:9312
	v_exp_f32_e32 v128, v128
	v_exp_f32_e32 v129, v129
	ds_read_b64 v[168:169], v247 offset:11520
	v_exp_f32_e32 v130, v130
	v_exp_f32_e32 v131, v131
	ds_read_b64 v[170:171], v247 offset:11552
	v_exp_f32_e32 v132, v132
	v_exp_f32_e32 v133, v133
	ds_read_b64 v[172:173], v247 offset:11584
	v_exp_f32_e32 v134, v134
	v_exp_f32_e32 v135, v135
	ds_read_b64 v[174:175], v247 offset:11616
	v_exp_f32_e32 v136, v136
	v_exp_f32_e32 v137, v137
	ds_read_b64 v[176:177], v247 offset:13824
	v_exp_f32_e32 v138, v138
	v_exp_f32_e32 v139, v139
	ds_read_b64 v[178:179], v247 offset:13856
	v_mul_f32_e32 v82, v82, v228
	v_add_f32_e32 v232, 0, v124
	ds_read_b64 v[180:181], v247 offset:13888
	v_add_f32_e32 v232, v232, v125
	v_add_f32_e32 v232, v232, v126
	ds_read_b64 v[182:183], v247 offset:13920
	v_add_f32_e32 v232, v232, v127
	v_add_f32_e32 v232, v232, v128
	ds_read_b64 v[184:185], v247 offset:16128
	v_add_f32_e32 v232, v232, v129
	v_add_f32_e32 v232, v232, v130
	ds_read_b64 v[186:187], v247 offset:16160
	v_add_f32_e32 v232, v232, v131
	v_add_f32_e32 v232, v232, v132
	ds_read_b64 v[188:189], v247 offset:16192
	v_add_f32_e32 v232, v232, v133
	v_add_f32_e32 v232, v232, v134
	ds_read_b64 v[190:191], v247 offset:16224
	v_add_f32_e32 v232, v232, v135
	v_add_f32_e32 v232, v232, v136
	v_add_f32_e32 v232, v232, v137
	v_add_f32_e32 v232, v232, v138
	v_add_f32_e32 v232, v232, v139
	v_add_f32_e32 v82, v82, v232
	v_pk_mul_f32 v[48:49], v[48:49], v[228:229] op_sel_hi:[1,0]
	v_pk_mul_f32 v[50:51], v[50:51], v[228:229] op_sel_hi:[1,0]
	v_pk_mul_f32 v[52:53], v[52:53], v[228:229] op_sel_hi:[1,0]
	v_pk_mul_f32 v[54:55], v[54:55], v[228:229] op_sel_hi:[1,0]
	v_pk_mul_f32 v[56:57], v[56:57], v[228:229] op_sel_hi:[1,0]
	v_pk_mul_f32 v[58:59], v[58:59], v[228:229] op_sel_hi:[1,0]
	v_pk_mul_f32 v[60:61], v[60:61], v[228:229] op_sel_hi:[1,0]
	v_pk_mul_f32 v[62:63], v[62:63], v[228:229] op_sel_hi:[1,0]
	v_cvt_pk_bf16_f32 v204, v124, v125
	v_cvt_pk_bf16_f32 v205, v126, v127
	v_cvt_pk_bf16_f32 v206, v128, v129
	v_cvt_pk_bf16_f32 v207, v130, v131
	v_cvt_pk_bf16_f32 v208, v132, v133
	v_cvt_pk_bf16_f32 v209, v134, v135
	v_cvt_pk_bf16_f32 v210, v136, v137
	v_cvt_pk_bf16_f32 v211, v138, v139
	s_cmp_eq_u32 s64, 0
	s_cbranch_scc1 .Lnsa_nm_19
	v_cndmask_b32_e64 v240, -1, v121, s[62:63]
	v_subrev_u32_e32 v220, 0, v240
	v_subrev_u32_e32 v221, 1, v240
	v_subrev_u32_e32 v222, 2, v240
	v_subrev_u32_e32 v223, 3, v240
	v_cmp_gt_u32_e64 s[52:53], s45, v220
	v_cmp_gt_u32_e64 s[54:55], s45, v221
	v_cmp_gt_u32_e64 s[56:57], s45, v222
	v_cmp_gt_u32_e64 s[58:59], s45, v223
	v_cndmask_b32_e64 v140, v224, v140, s[52:53]
	v_cndmask_b32_e64 v141, v224, v141, s[54:55]
	v_cndmask_b32_e64 v142, v224, v142, s[56:57]
	v_cndmask_b32_e64 v143, v224, v143, s[58:59]
	v_subrev_u32_e32 v220, 16, v240
	v_subrev_u32_e32 v221, 17, v240
	v_subrev_u32_e32 v222, 18, v240
	v_subrev_u32_e32 v223, 19, v240
	v_cmp_gt_u32_e64 s[52:53], s45, v220
	v_cmp_gt_u32_e64 s[54:55], s45, v221
	v_cmp_gt_u32_e64 s[56:57], s45, v222
	v_cmp_gt_u32_e64 s[58:59], s45, v223
	v_cndmask_b32_e64 v144, v224, v144, s[52:53]
	v_cndmask_b32_e64 v145, v224, v145, s[54:55]
	v_cndmask_b32_e64 v146, v224, v146, s[56:57]
	v_cndmask_b32_e64 v147, v224, v147, s[58:59]
	v_subrev_u32_e32 v220, 32, v240
	v_subrev_u32_e32 v221, 33, v240
	v_subrev_u32_e32 v222, 34, v240
	v_subrev_u32_e32 v223, 35, v240
	v_cmp_gt_u32_e64 s[52:53], s45, v220
	v_cmp_gt_u32_e64 s[54:55], s45, v221
	v_cmp_gt_u32_e64 s[56:57], s45, v222
	v_cmp_gt_u32_e64 s[58:59], s45, v223
	v_cndmask_b32_e64 v148, v224, v148, s[52:53]
	v_cndmask_b32_e64 v149, v224, v149, s[54:55]
	v_cndmask_b32_e64 v150, v224, v150, s[56:57]
	v_cndmask_b32_e64 v151, v224, v151, s[58:59]
	v_subrev_u32_e32 v220, 48, v240
	v_subrev_u32_e32 v221, 49, v240
	v_subrev_u32_e32 v222, 50, v240
	v_subrev_u32_e32 v223, 51, v240
	v_cmp_gt_u32_e64 s[52:53], s45, v220
	v_cmp_gt_u32_e64 s[54:55], s45, v221
	v_cmp_gt_u32_e64 s[56:57], s45, v222
	v_cmp_gt_u32_e64 s[58:59], s45, v223
	v_cndmask_b32_e64 v154, v224, v154, s[52:53]
	v_cndmask_b32_e64 v155, v224, v155, s[54:55]
	v_cndmask_b32_e64 v156, v224, v156, s[56:57]
	v_cndmask_b32_e64 v157, v224, v157, s[58:59]
.Lnsa_nm_19:
	s_waitcnt lgkmcnt(0)
	v_max3_f32 v220, v140, v141, v142
	v_max3_f32 v220, v220, v143, v144
	v_mfma_f32_16x16x32_bf16 v[48:51], v[160:163], v[204:207], v[48:51]
	v_max3_f32 v220, v220, v145, v146
	v_max3_f32 v220, v220, v147, v148
	v_max3_f32 v220, v220, v149, v150
	v_max3_f32 v220, v220, v151, v154
	v_max3_f32 v220, v220, v155, v156
	v_mfma_f32_16x16x32_bf16 v[52:55], v[168:171], v[204:207], v[52:55]
	v_max3_f32 v220, v220, v157, v226
	v_cndmask_b32_e64 v220, v226, v220, s[62:63]
	v_mov_b32_e32 v221, v220
	s_nop 1
	v_permlane16_swap_b32_e32 v220, v221
	v_mfma_f32_16x16x32_bf16 v[56:59], v[176:179], v[204:207], v[56:59]
	v_max_f32_e32 v220, v220, v221
	v_mov_b32_e32 v221, v220
	s_nop 1
	v_permlane32_swap_b32_e32 v220, v221
	v_max_f32_e32 v220, v220, v221
	v_mfma_f32_16x16x32_bf16 v[60:63], v[184:187], v[204:207], v[60:63]
	v_max_f32_e32 v222, v81, v220
	v_sub_f32_e32 v223, v81, v222
	v_exp_f32_e32 v230, v223
	v_mov_b32_e32 v81, v222
	v_cndmask_b32_e64 v222, v227, v222, s[62:63]
	v_mfma_f32_16x16x32_bf16 v[48:51], v[164:167], v[208:211], v[48:51]
	v_sub_f32_e32 v140, v140, v222
	v_sub_f32_e32 v141, v141, v222
	v_sub_f32_e32 v142, v142, v222
	v_sub_f32_e32 v143, v143, v222
	v_sub_f32_e32 v144, v144, v222
	v_mfma_f32_16x16x32_bf16 v[52:55], v[172:175], v[208:211], v[52:55]
	v_sub_f32_e32 v145, v145, v222
	v_sub_f32_e32 v146, v146, v222
	v_sub_f32_e32 v147, v147, v222
	v_sub_f32_e32 v148, v148, v222
	v_sub_f32_e32 v149, v149, v222
	v_mfma_f32_16x16x32_bf16 v[56:59], v[180:183], v[208:211], v[56:59]
	v_sub_f32_e32 v150, v150, v222
	v_sub_f32_e32 v151, v151, v222
	v_sub_f32_e32 v154, v154, v222
	v_sub_f32_e32 v155, v155, v222
	v_sub_f32_e32 v156, v156, v222
	v_mfma_f32_16x16x32_bf16 v[60:63], v[188:191], v[208:211], v[60:63]
	v_sub_f32_e32 v157, v157, v222
	v_exp_f32_e32 v140, v140
	v_exp_f32_e32 v141, v141
	v_exp_f32_e32 v142, v142
	v_exp_f32_e32 v143, v143
	v_exp_f32_e32 v144, v144
	v_exp_f32_e32 v145, v145
	v_exp_f32_e32 v146, v146
	v_exp_f32_e32 v147, v147
	v_exp_f32_e32 v148, v148
	v_exp_f32_e32 v149, v149
	v_exp_f32_e32 v150, v150
	v_exp_f32_e32 v151, v151
	v_exp_f32_e32 v154, v154
	v_exp_f32_e32 v155, v155
	v_exp_f32_e32 v156, v156
	v_exp_f32_e32 v157, v157
	v_mul_f32_e32 v83, v83, v230
	v_add_f32_e32 v232, 0, v140
	v_add_f32_e32 v232, v232, v141
	v_add_f32_e32 v232, v232, v142
	v_add_f32_e32 v232, v232, v143
	v_add_f32_e32 v232, v232, v144
	v_add_f32_e32 v232, v232, v145
	v_add_f32_e32 v232, v232, v146
	v_add_f32_e32 v232, v232, v147
	v_add_f32_e32 v232, v232, v148
	v_add_f32_e32 v232, v232, v149
	v_add_f32_e32 v232, v232, v150
	v_add_f32_e32 v232, v232, v151
	v_add_f32_e32 v232, v232, v154
	v_add_f32_e32 v232, v232, v155
	v_add_f32_e32 v232, v232, v156
	v_add_f32_e32 v232, v232, v157
	v_add_f32_e32 v83, v83, v232
	v_pk_mul_f32 v[64:65], v[64:65], v[230:231] op_sel_hi:[1,0]
	v_pk_mul_f32 v[66:67], v[66:67], v[230:231] op_sel_hi:[1,0]
	v_pk_mul_f32 v[68:69], v[68:69], v[230:231] op_sel_hi:[1,0]
	v_pk_mul_f32 v[70:71], v[70:71], v[230:231] op_sel_hi:[1,0]
	v_pk_mul_f32 v[72:73], v[72:73], v[230:231] op_sel_hi:[1,0]
	v_pk_mul_f32 v[74:75], v[74:75], v[230:231] op_sel_hi:[1,0]
	v_pk_mul_f32 v[76:77], v[76:77], v[230:231] op_sel_hi:[1,0]
	v_pk_mul_f32 v[78:79], v[78:79], v[230:231] op_sel_hi:[1,0]
	v_cvt_pk_bf16_f32 v212, v140, v141
	v_cvt_pk_bf16_f32 v213, v142, v143
	v_cvt_pk_bf16_f32 v214, v144, v145
	v_cvt_pk_bf16_f32 v215, v146, v147
	v_cvt_pk_bf16_f32 v216, v148, v149
	v_cvt_pk_bf16_f32 v217, v150, v151
	v_cvt_pk_bf16_f32 v218, v154, v155
	v_cvt_pk_bf16_f32 v219, v156, v157
	v_mfma_f32_16x16x32_bf16 v[64:67], v[160:163], v[212:215], v[64:67]
	v_mfma_f32_16x16x32_bf16 v[68:71], v[168:171], v[212:215], v[68:71]
	v_mfma_f32_16x16x32_bf16 v[72:75], v[176:179], v[212:215], v[72:75]
	v_mfma_f32_16x16x32_bf16 v[76:79], v[184:187], v[212:215], v[76:79]
	v_mfma_f32_16x16x32_bf16 v[64:67], v[164:167], v[216:219], v[64:67]
	v_mfma_f32_16x16x32_bf16 v[68:71], v[172:175], v[216:219], v[68:71]
	v_mfma_f32_16x16x32_bf16 v[72:75], v[180:183], v[216:219], v[72:75]
	v_mfma_f32_16x16x32_bf16 v[76:79], v[188:191], v[216:219], v[76:79]
	s_cmp_lt_i32 s41, 0
	s_cbranch_scc1 .Lnsa_brk_9
	s_or_b32 s65, s42, s40
	s_cmp_lt_i32 s65, 0
	s_cbranch_scc0 .Lnsa_w4_20
	s_waitcnt vmcnt(0)
	s_branch .Lnsa_wd_21

.Lnsa_nm_29:
	s_waitcnt lgkmcnt(0)
	v_max3_f32 v220, v140, v141, v142
	v_max3_f32 v220, v220, v143, v144
	v_mfma_f32_16x16x32_bf16 v[48:51], v[160:163], v[204:207], v[48:51]
	v_max3_f32 v220, v220, v145, v146
	v_max3_f32 v220, v220, v147, v148
	v_max3_f32 v220, v220, v149, v150
	v_max3_f32 v220, v220, v151, v154
	v_max3_f32 v220, v220, v155, v156
	v_mfma_f32_16x16x32_bf16 v[52:55], v[168:171], v[204:207], v[52:55]
	v_max3_f32 v220, v220, v157, v226
	v_cndmask_b32_e64 v220, v226, v220, s[62:63]
	v_mov_b32_e32 v221, v220
	s_nop 1
	v_permlane16_swap_b32_e32 v220, v221
	v_mfma_f32_16x16x32_bf16 v[56:59], v[176:179], v[204:207], v[56:59]
	v_max_f32_e32 v220, v220, v221
	v_mov_b32_e32 v221, v220
	s_nop 1
	v_permlane32_swap_b32_e32 v220, v221
	v_max_f32_e32 v220, v220, v221
	v_mfma_f32_16x16x32_bf16 v[60:63], v[184:187], v[204:207], v[60:63]
	v_max_f32_e32 v222, v81, v220
	v_sub_f32_e32 v223, v81, v222
	v_exp_f32_e32 v230, v223
	v_mov_b32_e32 v81, v222
	v_cndmask_b32_e64 v222, v227, v222, s[62:63]
	v_mfma_f32_16x16x32_bf16 v[48:51], v[164:167], v[208:211], v[48:51]
	v_sub_f32_e32 v140, v140, v222
	v_sub_f32_e32 v141, v141, v222
	v_sub_f32_e32 v142, v142, v222
	v_sub_f32_e32 v143, v143, v222
	v_sub_f32_e32 v144, v144, v222
	v_mfma_f32_16x16x32_bf16 v[52:55], v[172:175], v[208:211], v[52:55]
	v_sub_f32_e32 v145, v145, v222
	v_sub_f32_e32 v146, v146, v222
	v_sub_f32_e32 v147, v147, v222
	v_sub_f32_e32 v148, v148, v222
	v_sub_f32_e32 v149, v149, v222
	v_mfma_f32_16x16x32_bf16 v[56:59], v[180:183], v[208:211], v[56:59]
	v_sub_f32_e32 v150, v150, v222
	v_sub_f32_e32 v151, v151, v222
	v_sub_f32_e32 v154, v154, v222
	v_sub_f32_e32 v155, v155, v222
	v_sub_f32_e32 v156, v156, v222
	v_mfma_f32_16x16x32_bf16 v[60:63], v[188:191], v[208:211], v[60:63]
	v_sub_f32_e32 v157, v157, v222
	v_exp_f32_e32 v140, v140
	v_exp_f32_e32 v141, v141
	v_exp_f32_e32 v142, v142
	v_exp_f32_e32 v143, v143
	v_exp_f32_e32 v144, v144
	v_exp_f32_e32 v145, v145
	v_exp_f32_e32 v146, v146
	v_exp_f32_e32 v147, v147
	v_exp_f32_e32 v148, v148
	v_exp_f32_e32 v149, v149
	v_exp_f32_e32 v150, v150
	v_exp_f32_e32 v151, v151
	v_exp_f32_e32 v154, v154
	v_exp_f32_e32 v155, v155
	v_exp_f32_e32 v156, v156
	v_exp_f32_e32 v157, v157
	v_mul_f32_e32 v83, v83, v230
	v_add_f32_e32 v232, 0, v140
	v_add_f32_e32 v232, v232, v141
	v_add_f32_e32 v232, v232, v142
	v_add_f32_e32 v232, v232, v143
	v_add_f32_e32 v232, v232, v144
	v_add_f32_e32 v232, v232, v145
	v_add_f32_e32 v232, v232, v146
	v_add_f32_e32 v232, v232, v147
	v_add_f32_e32 v232, v232, v148
	v_add_f32_e32 v232, v232, v149
	v_add_f32_e32 v232, v232, v150
	v_add_f32_e32 v232, v232, v151
	v_add_f32_e32 v232, v232, v154
	v_add_f32_e32 v232, v232, v155
	v_add_f32_e32 v232, v232, v156
	v_add_f32_e32 v232, v232, v157
	v_add_f32_e32 v83, v83, v232
	v_pk_mul_f32 v[64:65], v[64:65], v[230:231] op_sel_hi:[1,0]
	v_pk_mul_f32 v[66:67], v[66:67], v[230:231] op_sel_hi:[1,0]
	v_pk_mul_f32 v[68:69], v[68:69], v[230:231] op_sel_hi:[1,0]
	v_pk_mul_f32 v[70:71], v[70:71], v[230:231] op_sel_hi:[1,0]
	v_pk_mul_f32 v[72:73], v[72:73], v[230:231] op_sel_hi:[1,0]
	v_pk_mul_f32 v[74:75], v[74:75], v[230:231] op_sel_hi:[1,0]
	v_pk_mul_f32 v[76:77], v[76:77], v[230:231] op_sel_hi:[1,0]
	v_pk_mul_f32 v[78:79], v[78:79], v[230:231] op_sel_hi:[1,0]
	v_cvt_pk_bf16_f32 v212, v140, v141
	v_cvt_pk_bf16_f32 v213, v142, v143
	v_cvt_pk_bf16_f32 v214, v144, v145
	v_cvt_pk_bf16_f32 v215, v146, v147
	v_cvt_pk_bf16_f32 v216, v148, v149
	v_cvt_pk_bf16_f32 v217, v150, v151
	v_cvt_pk_bf16_f32 v218, v154, v155
	v_cvt_pk_bf16_f32 v219, v156, v157
	v_mfma_f32_16x16x32_bf16 v[64:67], v[160:163], v[212:215], v[64:67]
	v_mfma_f32_16x16x32_bf16 v[68:71], v[168:171], v[212:215], v[68:71]
	v_mfma_f32_16x16x32_bf16 v[72:75], v[176:179], v[212:215], v[72:75]
	v_mfma_f32_16x16x32_bf16 v[76:79], v[184:187], v[212:215], v[76:79]
	v_mfma_f32_16x16x32_bf16 v[64:67], v[164:167], v[216:219], v[64:67]
	v_mfma_f32_16x16x32_bf16 v[68:71], v[172:175], v[216:219], v[68:71]
	v_mfma_f32_16x16x32_bf16 v[72:75], v[180:183], v[216:219], v[72:75]
	v_mfma_f32_16x16x32_bf16 v[76:79], v[188:191], v[216:219], v[76:79]
	s_cmp_lt_i32 s42, 0
	s_cbranch_scc1 .Lnsa_brk_9
	s_or_b32 s65, s40, s41
	s_cmp_lt_i32 s65, 0
	s_cbranch_scc0 .Lnsa_w4_30
	s_waitcnt vmcnt(0)
	s_branch .Lnsa_wd_31

.Lnsa_nm_39:
	s_waitcnt lgkmcnt(0)
	v_max3_f32 v220, v140, v141, v142
	v_max3_f32 v220, v220, v143, v144
	v_mfma_f32_16x16x32_bf16 v[48:51], v[160:163], v[204:207], v[48:51]
	v_max3_f32 v220, v220, v145, v146
	v_max3_f32 v220, v220, v147, v148
	v_max3_f32 v220, v220, v149, v150
	v_max3_f32 v220, v220, v151, v154
	v_max3_f32 v220, v220, v155, v156
	v_mfma_f32_16x16x32_bf16 v[52:55], v[168:171], v[204:207], v[52:55]
	v_max3_f32 v220, v220, v157, v226
	v_cndmask_b32_e64 v220, v226, v220, s[62:63]
	v_mov_b32_e32 v221, v220
	s_nop 1
	v_permlane16_swap_b32_e32 v220, v221
	v_mfma_f32_16x16x32_bf16 v[56:59], v[176:179], v[204:207], v[56:59]
	v_max_f32_e32 v220, v220, v221
	v_mov_b32_e32 v221, v220
	s_nop 1
	v_permlane32_swap_b32_e32 v220, v221
	v_max_f32_e32 v220, v220, v221
	v_mfma_f32_16x16x32_bf16 v[60:63], v[184:187], v[204:207], v[60:63]
	v_max_f32_e32 v222, v81, v220
	v_sub_f32_e32 v223, v81, v222
	v_exp_f32_e32 v230, v223
	v_mov_b32_e32 v81, v222
	v_cndmask_b32_e64 v222, v227, v222, s[62:63]
	v_mfma_f32_16x16x32_bf16 v[48:51], v[164:167], v[208:211], v[48:51]
	v_sub_f32_e32 v140, v140, v222
	v_sub_f32_e32 v141, v141, v222
	v_sub_f32_e32 v142, v142, v222
	v_sub_f32_e32 v143, v143, v222
	v_sub_f32_e32 v144, v144, v222
	v_mfma_f32_16x16x32_bf16 v[52:55], v[172:175], v[208:211], v[52:55]
	v_sub_f32_e32 v145, v145, v222
	v_sub_f32_e32 v146, v146, v222
	v_sub_f32_e32 v147, v147, v222
	v_sub_f32_e32 v148, v148, v222
	v_sub_f32_e32 v149, v149, v222
	v_mfma_f32_16x16x32_bf16 v[56:59], v[180:183], v[208:211], v[56:59]
	v_sub_f32_e32 v150, v150, v222
	v_sub_f32_e32 v151, v151, v222
	v_sub_f32_e32 v154, v154, v222
	v_sub_f32_e32 v155, v155, v222
	v_sub_f32_e32 v156, v156, v222
	v_mfma_f32_16x16x32_bf16 v[60:63], v[188:191], v[208:211], v[60:63]
	v_sub_f32_e32 v157, v157, v222
	v_exp_f32_e32 v140, v140
	v_exp_f32_e32 v141, v141
	v_exp_f32_e32 v142, v142
	v_exp_f32_e32 v143, v143
	v_exp_f32_e32 v144, v144
	v_exp_f32_e32 v145, v145
	v_exp_f32_e32 v146, v146
	v_exp_f32_e32 v147, v147
	v_exp_f32_e32 v148, v148
	v_exp_f32_e32 v149, v149
	v_exp_f32_e32 v150, v150
	v_exp_f32_e32 v151, v151
	v_exp_f32_e32 v154, v154
	v_exp_f32_e32 v155, v155
	v_exp_f32_e32 v156, v156
	v_exp_f32_e32 v157, v157
	v_mul_f32_e32 v83, v83, v230
	v_add_f32_e32 v232, 0, v140
	v_add_f32_e32 v232, v232, v141
	v_add_f32_e32 v232, v232, v142
	v_add_f32_e32 v232, v232, v143
	v_add_f32_e32 v232, v232, v144
	v_add_f32_e32 v232, v232, v145
	v_add_f32_e32 v232, v232, v146
	v_add_f32_e32 v232, v232, v147
	v_add_f32_e32 v232, v232, v148
	v_add_f32_e32 v232, v232, v149
	v_add_f32_e32 v232, v232, v150
	v_add_f32_e32 v232, v232, v151
	v_add_f32_e32 v232, v232, v154
	v_add_f32_e32 v232, v232, v155
	v_add_f32_e32 v232, v232, v156
	v_add_f32_e32 v232, v232, v157
	v_add_f32_e32 v83, v83, v232
	v_pk_mul_f32 v[64:65], v[64:65], v[230:231] op_sel_hi:[1,0]
	v_pk_mul_f32 v[66:67], v[66:67], v[230:231] op_sel_hi:[1,0]
	v_pk_mul_f32 v[68:69], v[68:69], v[230:231] op_sel_hi:[1,0]
	v_pk_mul_f32 v[70:71], v[70:71], v[230:231] op_sel_hi:[1,0]
	v_pk_mul_f32 v[72:73], v[72:73], v[230:231] op_sel_hi:[1,0]
	v_pk_mul_f32 v[74:75], v[74:75], v[230:231] op_sel_hi:[1,0]
	v_pk_mul_f32 v[76:77], v[76:77], v[230:231] op_sel_hi:[1,0]
	v_pk_mul_f32 v[78:79], v[78:79], v[230:231] op_sel_hi:[1,0]
	v_cvt_pk_bf16_f32 v212, v140, v141
	v_cvt_pk_bf16_f32 v213, v142, v143
	v_cvt_pk_bf16_f32 v214, v144, v145
	v_cvt_pk_bf16_f32 v215, v146, v147
	v_cvt_pk_bf16_f32 v216, v148, v149
	v_cvt_pk_bf16_f32 v217, v150, v151
	v_cvt_pk_bf16_f32 v218, v154, v155
	v_cvt_pk_bf16_f32 v219, v156, v157
	v_mfma_f32_16x16x32_bf16 v[64:67], v[160:163], v[212:215], v[64:67]
	v_mfma_f32_16x16x32_bf16 v[68:71], v[168:171], v[212:215], v[68:71]
	v_mfma_f32_16x16x32_bf16 v[72:75], v[176:179], v[212:215], v[72:75]
	v_mfma_f32_16x16x32_bf16 v[76:79], v[184:187], v[212:215], v[76:79]
	v_mfma_f32_16x16x32_bf16 v[64:67], v[164:167], v[216:219], v[64:67]
	v_mfma_f32_16x16x32_bf16 v[68:71], v[172:175], v[216:219], v[68:71]
	v_mfma_f32_16x16x32_bf16 v[72:75], v[180:183], v[216:219], v[72:75]
	v_mfma_f32_16x16x32_bf16 v[76:79], v[188:191], v[216:219], v[76:79]
	s_branch .Lnsa_loop_8
